# code placement mirror: every MFMA block of the hot K-loops starts at byte offset 4 mod 8
# speedup vs baseline: 1.0066x; 1.0066x over previous
; #define PG8_STAGE(bufoff, gbase, voff) do { _Pragma("unroll") for (int _i = 0; _i < 2; ++_i) \
;         __builtin_amdgcn_global_load_lds((const unsigned*)((const char*)(gbase) + (voff)[_i]), (LAS unsigned*)(lds + (bufoff) + ldsw + _i * 8192), 16, 0, 0); } while (0)
; #define PG8_LDA(dst, b, h) do { _Pragma("unroll") for (int m = 0; m < 4; ++m) _Pragma("unroll") for (int k = 0; k < 2; ++k) dst[m][k] = *(const LAS bf16x8*)(lds + PG8_SA(b, h) + aoff + m * 2048 + k * 1024); } while (0)
; #define PG8_LDB(dst, b, h) do { _Pragma("unroll") for (int n = 0; n < 2; ++n) _Pragma("unroll") for (int k = 0; k < 2; ++k) dst[n][k] = *(const LAS bf16x8*)(lds + PG8_SB(b, h) + boff + n * 2048 + k * 1024); } while (0)
; #define PG8_MMA(ai, bj, At, Bt) do { __builtin_amdgcn_s_setprio(1); _Pragma("unroll") for (int m = 0; m < 4; ++m) _Pragma("unroll") for (int n = 0; n < 2; ++n) _Pragma("unroll") for (int k = 0; k < 2; ++k) \
;         acc[ai][bj][m][n] = __builtin_amdgcn_mfma_f32_16x16x32_bf16(Bt[n][k], At[m][k], acc[ai][bj][m][n], 0, 0, 0); __builtin_amdgcn_s_setprio(0); } while (0)
; template <class Epi, class Sched>
; __device__ __forceinline__ void gemm_phase(LAS unsigned char* lds, const Gemm g, const Sched& S, const Epi& E) {
;     ...
;         const bool has_next = S.next(ui + 1, nxt);
;         const char* nA = has_next ? (const char*)g.A + (size_t)nxt.pm * tstepA + (size_t)nxt.pn * g.a_pn_off * 2 : cA; const char* nB = has_next ? (const char*)g.Bt + (size_t)nxt.pn * tstepB : cB;
;         for (int t = 0; t < nt; t += 2) {
;             const bool last = (t == nt - 2);
;             const char* a1 = cA + (size_t)(t + 1) * kstep;
;             const char* a2 = last ? nA : cA + (size_t)(t + 2) * kstep; const char* b2 = last ? nB : cB + (size_t)(t + 2) * kstep;
;             const char* a3 = a2 + kstep; const char* b3 = b2 + kstep;
;             PG8_LDB(B0, 0, 0); PG8_LDB(B1, 0, 1); PG8_SCHED; PG8_LDA(At, 0, 0); PG8_STAGE(PG8_SA(1, 1), a1 + hstepA, voffA);
;             PG8_WAIT_V(8); PG8_WAIT_L(0); PG8_BAR; PG8_MMA(0, 0, At, B0); PG8_MMA(0, 1, At, B1); PG8_BAR; PG8_SCHED;
;             PG8_LDA(At, 0, 1); PG8_STAGE(PG8_SB(0, 0), b2, voffB); PG8_STAGE(PG8_SB(0, 1), b2 + hstepB, voffB); PG8_STAGE(PG8_SA(0, 0), a2, voffA);
;             PG8_WAIT_V(8); PG8_WAIT_L(0); PG8_BAR; PG8_MMA(1, 0, At, B0); PG8_MMA(1, 1, At, B1); PG8_BAR; PG8_SCHED;
.LBB0_231:
	s_ashr_i32 s83, s82, 31
	s_lshl_b64 s[36:37], s[82:83], 19
	s_add_u32 s84, s4, s36
	s_addc_u32 s85, s5, s37
	s_and_b64 s[36:37], s[70:71], exec
	s_cselect_b32 s43, s85, s19
	s_cselect_b32 s48, s84, s18
	s_ashr_i32 s81, s80, 31
	s_lshl_b64 s[36:37], s[80:81], 19
	v_readlane_b32 s12, v248, 5
	s_add_u32 s36, s12, s36
	v_readlane_b32 s12, v248, 6
	s_addc_u32 s37, s12, s37
	s_and_b64 s[86:87], s[70:71], exec
	s_cselect_b32 s49, s37, s21
	s_cselect_b32 s53, s36, s20
	s_add_u32 s18, s18, 0x40080
	s_addc_u32 s19, s19, 0
	s_add_u32 s54, s20, 0x100
	s_addc_u32 s81, s21, 0
	s_mov_b32 s83, -2
	s_add_u32 s20, s18, 0xfffc0080
	s_addc_u32 s21, s19, -1
	s_add_i32 s88, 0, 0x10000
	s_cmp_eq_u32 s83, 12
	s_cselect_b32 s21, s43, s21
	s_cselect_b32 s20, s48, s20
	s_cselect_b32 s87, s49, s81
	s_cselect_b32 s86, s53, s54
	s_add_i32 s90, 0, 0x14000
	s_add_u32 s100, s20, 0x80
	s_addc_u32 s101, s21, 0
	s_add_i32 m0, s9, 0xc000
	s_nop 0
	global_load_lds_dwordx4 v170, s[18:19]
	s_add_i32 m0, s9, 0xe000
	s_nop 0
	global_load_lds_dwordx4 v190, s[18:19]
	ds_read_b128 v[130:133], v246
	ds_read_b128 v[134:137], v246 offset:1024
	ds_read_b128 v[138:141], v246 offset:2048
	ds_read_b128 v[142:145], v246 offset:3072
	ds_read_b128 v[146:149], v246 offset:16384
	ds_read_b128 v[150:153], v246 offset:17408
	ds_read_b128 v[154:157], v246 offset:18432
	ds_read_b128 v[158:161], v246 offset:19456
	ds_read_b128 v[162:165], v222
	ds_read_b128 v[166:169], v222 offset:1024
	ds_read_b128 v[194:197], v222 offset:2048
	ds_read_b128 v[198:201], v222 offset:3072
	ds_read_b128 v[202:205], v222 offset:4096
	ds_read_b128 v[224:227], v222 offset:5120
	ds_read_b128 v[228:231], v222 offset:6144
	ds_read_b128 v[232:235], v222 offset:7168
	s_waitcnt vmcnt(8)
	s_waitcnt lgkmcnt(0)
	s_barrier
	s_waitcnt lgkmcnt(0)
	v_mfma_f32_16x16x32_bf16 v[126:129], v[130:133], v[162:165], 0
	v_mfma_f32_16x16x32_bf16 v[118:121], v[138:141], v[162:165], 0
	v_mfma_f32_16x16x32_bf16 v[110:113], v[130:133], v[194:197], 0
	v_mfma_f32_16x16x32_bf16 v[102:105], v[138:141], v[194:197], 0
	v_mfma_f32_16x16x32_bf16 v[94:97], v[130:133], v[202:205], 0
	v_mfma_f32_16x16x32_bf16 v[86:89], v[138:141], v[202:205], 0
	v_mfma_f32_16x16x32_bf16 v[78:81], v[130:133], v[228:231], 0
	v_mfma_f32_16x16x32_bf16 v[70:73], v[138:141], v[228:231], 0
	v_mfma_f32_16x16x32_bf16 v[126:129], v[134:137], v[166:169], v[126:129]
	v_mfma_f32_16x16x32_bf16 v[118:121], v[142:145], v[166:169], v[118:121]
	v_mfma_f32_16x16x32_bf16 v[110:113], v[134:137], v[198:201], v[110:113]
	v_mfma_f32_16x16x32_bf16 v[102:105], v[142:145], v[198:201], v[102:105]
	v_mfma_f32_16x16x32_bf16 v[94:97], v[134:137], v[224:227], v[94:97]
	v_mfma_f32_16x16x32_bf16 v[86:89], v[142:145], v[224:227], v[86:89]
	v_mfma_f32_16x16x32_bf16 v[78:81], v[134:137], v[232:235], v[78:81]
	v_mfma_f32_16x16x32_bf16 v[70:73], v[142:145], v[232:235], v[70:73]
	v_mfma_f32_16x16x32_bf16 v[122:125], v[146:149], v[162:165], 0
	v_mfma_f32_16x16x32_bf16 v[114:117], v[154:157], v[162:165], 0
	v_mfma_f32_16x16x32_bf16 v[106:109], v[146:149], v[194:197], 0
	v_mfma_f32_16x16x32_bf16 v[98:101], v[154:157], v[194:197], 0
	v_mfma_f32_16x16x32_bf16 v[90:93], v[146:149], v[202:205], 0
	v_mfma_f32_16x16x32_bf16 v[82:85], v[154:157], v[202:205], 0
	v_mfma_f32_16x16x32_bf16 v[74:77], v[146:149], v[228:231], 0
	v_mfma_f32_16x16x32_bf16 v[66:69], v[154:157], v[228:231], 0
	v_mfma_f32_16x16x32_bf16 v[122:125], v[150:153], v[166:169], v[122:125]
	v_mfma_f32_16x16x32_bf16 v[114:117], v[158:161], v[166:169], v[114:117]
	v_mfma_f32_16x16x32_bf16 v[106:109], v[150:153], v[198:201], v[106:109]
	v_mfma_f32_16x16x32_bf16 v[98:101], v[158:161], v[198:201], v[98:101]
	v_mfma_f32_16x16x32_bf16 v[90:93], v[150:153], v[224:227], v[90:93]
	v_mfma_f32_16x16x32_bf16 v[82:85], v[158:161], v[224:227], v[82:85]
	v_mfma_f32_16x16x32_bf16 v[74:77], v[150:153], v[232:235], v[74:77]
	v_mfma_f32_16x16x32_bf16 v[66:69], v[158:161], v[232:235], v[66:69]
	s_barrier
	s_add_i32 s88, s88, s8
	s_mov_b32 m0, s88
	s_nop 0
	global_load_lds_dwordx4 v172, s[86:87]
	s_add_i32 m0, s88, 0x2000
	s_add_u32 s88, s86, 0x40000
	s_addc_u32 s89, s87, 0
	s_add_i32 s90, s90, s8
	global_load_lds_dwordx4 v192, s[86:87]
	s_mov_b32 m0, s90
	s_nop 0
	global_load_lds_dwordx4 v172, s[88:89]
	s_add_i32 m0, s90, 0x2000
	s_nop 0
	global_load_lds_dwordx4 v192, s[88:89]
	s_mov_b32 m0, s9
	s_nop 0
	global_load_lds_dwordx4 v170, s[20:21]
	s_mov_b32 m0, s28
	s_nop 0
	global_load_lds_dwordx4 v190, s[20:21]
	ds_read_b128 v[162:165], v222 offset:16384
	ds_read_b128 v[166:169], v222 offset:17408
	ds_read_b128 v[194:197], v222 offset:18432
	ds_read_b128 v[198:201], v222 offset:19456
	ds_read_b128 v[202:205], v222 offset:20480
	ds_read_b128 v[224:227], v222 offset:21504
	ds_read_b128 v[228:231], v222 offset:22528
	ds_read_b128 v[232:235], v222 offset:23552
	s_waitcnt vmcnt(8)
	s_waitcnt lgkmcnt(0)
	s_nop 0
	s_barrier
; #define PG8_STAGE(bufoff, gbase, voff) do { _Pragma("unroll") for (int _i = 0; _i < 2; ++_i) \
;         __builtin_amdgcn_global_load_lds((const unsigned*)((const char*)(gbase) + (voff)[_i]), (LAS unsigned*)(lds + (bufoff) + ldsw + _i * 8192), 16, 0, 0); } while (0)
; #define PG8_LDA(dst, b, h) do { _Pragma("unroll") for (int m = 0; m < 4; ++m) _Pragma("unroll") for (int k = 0; k < 2; ++k) dst[m][k] = *(const LAS bf16x8*)(lds + PG8_SA(b, h) + aoff + m * 2048 + k * 1024); } while (0)
; #define PG8_LDB(dst, b, h) do { _Pragma("unroll") for (int n = 0; n < 2; ++n) _Pragma("unroll") for (int k = 0; k < 2; ++k) dst[n][k] = *(const LAS bf16x8*)(lds + PG8_SB(b, h) + boff + n * 2048 + k * 1024); } while (0)
; #define PG8_MMA(ai, bj, At, Bt) do { __builtin_amdgcn_s_setprio(1); _Pragma("unroll") for (int m = 0; m < 4; ++m) _Pragma("unroll") for (int n = 0; n < 2; ++n) _Pragma("unroll") for (int k = 0; k < 2; ++k) \
;         acc[ai][bj][m][n] = __builtin_amdgcn_mfma_f32_16x16x32_bf16(Bt[n][k], At[m][k], acc[ai][bj][m][n], 0, 0, 0); __builtin_amdgcn_s_setprio(0); } while (0)
; #define PG8_WAIT_V(n) asm volatile("s_waitcnt vmcnt(" #n ")" ::: "memory")
; #define PG8_WAIT_L(n) asm volatile("s_waitcnt lgkmcnt(" #n ")" ::: "memory")
; #define PG8_BAR __builtin_amdgcn_s_barrier()
; #define PG8_SCHED __builtin_amdgcn_sched_barrier(0)
; template <class Epi, class Sched>
; __device__ __forceinline__ void gemm_phase(LAS unsigned char* lds, const Gemm g, const Sched& S, const Epi& E) {
;     ...
;             PG8_LDA(At, 0, 1); PG8_STAGE(PG8_SB(0, 0), b2, voffB); PG8_STAGE(PG8_SB(0, 1), b2 + hstepB, voffB); PG8_STAGE(PG8_SA(0, 0), a2, voffA);
;             PG8_WAIT_V(8); PG8_WAIT_L(0); PG8_BAR; PG8_MMA(1, 0, At, B0); PG8_MMA(1, 1, At, B1); PG8_BAR; PG8_SCHED;
;             PG8_LDB(B0, 1, 0); PG8_LDB(B1, 1, 1); PG8_SCHED; PG8_LDA(At, 1, 0); PG8_STAGE(PG8_SA(0, 1), a2 + hstepA, voffA);
;             PG8_WAIT_V(8); PG8_WAIT_L(0); PG8_BAR; PG8_MMA(0, 0, At, B0); PG8_MMA(0, 1, At, B1); PG8_BAR; PG8_SCHED;
	s_waitcnt lgkmcnt(0)
	v_mfma_f32_16x16x32_bf16 v[62:65], v[130:133], v[162:165], 0
	v_mfma_f32_16x16x32_bf16 v[54:57], v[138:141], v[162:165], 0
	v_mfma_f32_16x16x32_bf16 v[46:49], v[130:133], v[194:197], 0
	v_mfma_f32_16x16x32_bf16 v[38:41], v[138:141], v[194:197], 0
	v_mfma_f32_16x16x32_bf16 v[30:33], v[130:133], v[202:205], 0
	v_mfma_f32_16x16x32_bf16 v[22:25], v[138:141], v[202:205], 0
	v_mfma_f32_16x16x32_bf16 v[14:17], v[130:133], v[228:231], 0
	v_mfma_f32_16x16x32_bf16 v[6:9], v[138:141], v[228:231], 0
	v_mfma_f32_16x16x32_bf16 v[62:65], v[134:137], v[166:169], v[62:65]
	v_mfma_f32_16x16x32_bf16 v[54:57], v[142:145], v[166:169], v[54:57]
	v_mfma_f32_16x16x32_bf16 v[46:49], v[134:137], v[198:201], v[46:49]
	v_mfma_f32_16x16x32_bf16 v[38:41], v[142:145], v[198:201], v[38:41]
	v_mfma_f32_16x16x32_bf16 v[30:33], v[134:137], v[224:227], v[30:33]
	v_mfma_f32_16x16x32_bf16 v[22:25], v[142:145], v[224:227], v[22:25]
	v_mfma_f32_16x16x32_bf16 v[14:17], v[134:137], v[232:235], v[14:17]
	v_mfma_f32_16x16x32_bf16 v[6:9], v[142:145], v[232:235], v[6:9]
	v_mfma_f32_16x16x32_bf16 v[58:61], v[146:149], v[162:165], 0
	v_mfma_f32_16x16x32_bf16 v[50:53], v[154:157], v[162:165], 0
	v_mfma_f32_16x16x32_bf16 v[42:45], v[146:149], v[194:197], 0
	v_mfma_f32_16x16x32_bf16 v[34:37], v[154:157], v[194:197], 0
	v_mfma_f32_16x16x32_bf16 v[26:29], v[146:149], v[202:205], 0
	v_mfma_f32_16x16x32_bf16 v[18:21], v[154:157], v[202:205], 0
	v_mfma_f32_16x16x32_bf16 v[10:13], v[146:149], v[228:231], 0
	v_mfma_f32_16x16x32_bf16 v[2:5], v[154:157], v[228:231], 0
	v_mfma_f32_16x16x32_bf16 v[58:61], v[150:153], v[166:169], v[58:61]
	v_mfma_f32_16x16x32_bf16 v[50:53], v[158:161], v[166:169], v[50:53]
	v_mfma_f32_16x16x32_bf16 v[42:45], v[150:153], v[198:201], v[42:45]
	v_mfma_f32_16x16x32_bf16 v[34:37], v[158:161], v[198:201], v[34:37]
	v_mfma_f32_16x16x32_bf16 v[26:29], v[150:153], v[224:227], v[26:29]
	v_mfma_f32_16x16x32_bf16 v[18:21], v[158:161], v[224:227], v[18:21]
	v_mfma_f32_16x16x32_bf16 v[10:13], v[150:153], v[232:235], v[10:13]
	v_mfma_f32_16x16x32_bf16 v[2:5], v[158:161], v[232:235], v[2:5]
	s_barrier
	s_add_i32 s88, 0, 0x18000
	s_add_i32 s89, 0, 0x1c000
	s_add_u32 s20, s20, 0x40000
	s_addc_u32 s21, s21, 0
	s_mov_b32 m0, s29
	s_nop 0
	global_load_lds_dwordx4 v170, s[20:21]
	s_mov_b32 m0, s30
	s_nop 0
	global_load_lds_dwordx4 v190, s[20:21]
	ds_read_b128 v[130:133], v246 offset:32768
	ds_read_b128 v[134:137], v246 offset:33792
	ds_read_b128 v[138:141], v246 offset:34816
	ds_read_b128 v[142:145], v246 offset:35840
	ds_read_b128 v[146:149], v246 offset:49152
	ds_read_b128 v[150:153], v246 offset:50176
	ds_read_b128 v[154:157], v246 offset:51200
	ds_read_b128 v[158:161], v246 offset:52224
	ds_read_b128 v[162:165], v222 offset:32768
	ds_read_b128 v[166:169], v222 offset:33792
	ds_read_b128 v[194:197], v222 offset:34816
	ds_read_b128 v[198:201], v222 offset:35840
	ds_read_b128 v[202:205], v222 offset:36864
	ds_read_b128 v[224:227], v222 offset:37888
	ds_read_b128 v[228:231], v222 offset:38912
	ds_read_b128 v[232:235], v222 offset:39936
	s_waitcnt vmcnt(8)
	s_waitcnt lgkmcnt(0)
	s_barrier
	s_waitcnt lgkmcnt(0)
	v_mfma_f32_16x16x32_bf16 v[126:129], v[130:133], v[162:165], v[126:129]
	v_mfma_f32_16x16x32_bf16 v[118:121], v[138:141], v[162:165], v[118:121]
	v_mfma_f32_16x16x32_bf16 v[110:113], v[130:133], v[194:197], v[110:113]
	v_mfma_f32_16x16x32_bf16 v[102:105], v[138:141], v[194:197], v[102:105]
	v_mfma_f32_16x16x32_bf16 v[94:97], v[130:133], v[202:205], v[94:97]
	v_mfma_f32_16x16x32_bf16 v[86:89], v[138:141], v[202:205], v[86:89]
	v_mfma_f32_16x16x32_bf16 v[78:81], v[130:133], v[228:231], v[78:81]
	v_mfma_f32_16x16x32_bf16 v[70:73], v[138:141], v[228:231], v[70:73]
	v_mfma_f32_16x16x32_bf16 v[126:129], v[134:137], v[166:169], v[126:129]
	v_mfma_f32_16x16x32_bf16 v[118:121], v[142:145], v[166:169], v[118:121]
	v_mfma_f32_16x16x32_bf16 v[110:113], v[134:137], v[198:201], v[110:113]
	v_mfma_f32_16x16x32_bf16 v[102:105], v[142:145], v[198:201], v[102:105]
	v_mfma_f32_16x16x32_bf16 v[94:97], v[134:137], v[224:227], v[94:97]
	v_mfma_f32_16x16x32_bf16 v[86:89], v[142:145], v[224:227], v[86:89]
	v_mfma_f32_16x16x32_bf16 v[78:81], v[134:137], v[232:235], v[78:81]
	v_mfma_f32_16x16x32_bf16 v[70:73], v[142:145], v[232:235], v[70:73]
	v_mfma_f32_16x16x32_bf16 v[122:125], v[146:149], v[162:165], v[122:125]
	v_mfma_f32_16x16x32_bf16 v[114:117], v[154:157], v[162:165], v[114:117]
	v_mfma_f32_16x16x32_bf16 v[106:109], v[146:149], v[194:197], v[106:109]
	v_mfma_f32_16x16x32_bf16 v[98:101], v[154:157], v[194:197], v[98:101]
	v_mfma_f32_16x16x32_bf16 v[90:93], v[146:149], v[202:205], v[90:93]
	v_mfma_f32_16x16x32_bf16 v[82:85], v[154:157], v[202:205], v[82:85]
	v_mfma_f32_16x16x32_bf16 v[74:77], v[146:149], v[228:231], v[74:77]
	v_mfma_f32_16x16x32_bf16 v[66:69], v[154:157], v[228:231], v[66:69]
	v_mfma_f32_16x16x32_bf16 v[122:125], v[150:153], v[166:169], v[122:125]
	v_mfma_f32_16x16x32_bf16 v[114:117], v[158:161], v[166:169], v[114:117]
	v_mfma_f32_16x16x32_bf16 v[106:109], v[150:153], v[198:201], v[106:109]
	v_mfma_f32_16x16x32_bf16 v[98:101], v[158:161], v[198:201], v[98:101]
	v_mfma_f32_16x16x32_bf16 v[90:93], v[150:153], v[224:227], v[90:93]
	v_mfma_f32_16x16x32_bf16 v[82:85], v[158:161], v[224:227], v[82:85]
	v_mfma_f32_16x16x32_bf16 v[74:77], v[150:153], v[232:235], v[74:77]
	v_mfma_f32_16x16x32_bf16 v[66:69], v[158:161], v[232:235], v[66:69]
	s_barrier
; #define PG8_STAGE(bufoff, gbase, voff) do { _Pragma("unroll") for (int _i = 0; _i < 2; ++_i) \
;         __builtin_amdgcn_global_load_lds((const unsigned*)((const char*)(gbase) + (voff)[_i]), (LAS unsigned*)(lds + (bufoff) + ldsw + _i * 8192), 16, 0, 0); } while (0)
; #define PG8_LDA(dst, b, h) do { _Pragma("unroll") for (int m = 0; m < 4; ++m) _Pragma("unroll") for (int k = 0; k < 2; ++k) dst[m][k] = *(const LAS bf16x8*)(lds + PG8_SA(b, h) + aoff + m * 2048 + k * 1024); } while (0)
; #define PG8_MMA(ai, bj, At, Bt) do { __builtin_amdgcn_s_setprio(1); _Pragma("unroll") for (int m = 0; m < 4; ++m) _Pragma("unroll") for (int n = 0; n < 2; ++n) _Pragma("unroll") for (int k = 0; k < 2; ++k) \
;         acc[ai][bj][m][n] = __builtin_amdgcn_mfma_f32_16x16x32_bf16(Bt[n][k], At[m][k], acc[ai][bj][m][n], 0, 0, 0); __builtin_amdgcn_s_setprio(0); } while (0)
; #define PG8_WAIT_V(n) asm volatile("s_waitcnt vmcnt(" #n ")" ::: "memory")
; #define PG8_WAIT_L(n) asm volatile("s_waitcnt lgkmcnt(" #n ")" ::: "memory")
; #define PG8_BAR __builtin_amdgcn_s_barrier()
; #define PG8_SCHED __builtin_amdgcn_sched_barrier(0)
; template <class Epi, class Sched>
; __device__ __forceinline__ void gemm_phase(LAS unsigned char* lds, const Gemm g, const Sched& S, const Epi& E) {
;     ...
;             PG8_LDA(At, 1, 1); PG8_STAGE(PG8_SB(1, 0), b3, voffB); PG8_STAGE(PG8_SB(1, 1), b3 + hstepB, voffB); PG8_STAGE(PG8_SA(1, 0), a3, voffA);
;             PG8_WAIT_V(8); PG8_WAIT_L(0); PG8_BAR; PG8_MMA(1, 0, At, B0); PG8_MMA(1, 1, At, B1); PG8_BAR; PG8_SCHED;
;         }
	s_add_i32 s20, s8, 0x18000
	s_add_u32 s88, s86, 0x80
	s_addc_u32 s89, s87, 0
	s_mov_b32 m0, s20
	s_nop 0
	global_load_lds_dwordx4 v172, s[88:89]
	s_add_i32 m0, s20, 0x2000
	s_add_u32 s20, s86, 0x40080
	s_addc_u32 s21, s87, 0
	s_add_i32 s12, s8, 0x1c000
	global_load_lds_dwordx4 v192, s[88:89]
	s_mov_b32 m0, s12
	s_nop 0
	global_load_lds_dwordx4 v172, s[20:21]
	s_add_i32 m0, s12, 0x2000
	s_nop 0
	global_load_lds_dwordx4 v192, s[20:21]
	s_mov_b32 m0, s31
	s_nop 0
	global_load_lds_dwordx4 v170, s[100:101]
	s_mov_b32 m0, s34
	s_nop 0
	global_load_lds_dwordx4 v190, s[100:101]
	ds_read_b128 v[162:165], v222 offset:49152
	ds_read_b128 v[166:169], v222 offset:50176
	ds_read_b128 v[194:197], v222 offset:51200
	ds_read_b128 v[198:201], v222 offset:52224
	ds_read_b128 v[202:205], v222 offset:53248
	ds_read_b128 v[224:227], v222 offset:54272
	ds_read_b128 v[228:231], v222 offset:55296
	ds_read_b128 v[232:235], v222 offset:56320
	s_waitcnt vmcnt(8)
	s_waitcnt lgkmcnt(0)
	s_barrier
	s_waitcnt lgkmcnt(0)
	v_mfma_f32_16x16x32_bf16 v[62:65], v[130:133], v[162:165], v[62:65]
	v_mfma_f32_16x16x32_bf16 v[54:57], v[138:141], v[162:165], v[54:57]
	v_mfma_f32_16x16x32_bf16 v[46:49], v[130:133], v[194:197], v[46:49]
	v_mfma_f32_16x16x32_bf16 v[38:41], v[138:141], v[194:197], v[38:41]
	v_mfma_f32_16x16x32_bf16 v[30:33], v[130:133], v[202:205], v[30:33]
	v_mfma_f32_16x16x32_bf16 v[22:25], v[138:141], v[202:205], v[22:25]
	v_mfma_f32_16x16x32_bf16 v[14:17], v[130:133], v[228:231], v[14:17]
	v_mfma_f32_16x16x32_bf16 v[6:9], v[138:141], v[228:231], v[6:9]
	v_mfma_f32_16x16x32_bf16 v[62:65], v[134:137], v[166:169], v[62:65]
	v_mfma_f32_16x16x32_bf16 v[54:57], v[142:145], v[166:169], v[54:57]
	v_mfma_f32_16x16x32_bf16 v[46:49], v[134:137], v[198:201], v[46:49]
	v_mfma_f32_16x16x32_bf16 v[38:41], v[142:145], v[198:201], v[38:41]
	v_mfma_f32_16x16x32_bf16 v[30:33], v[134:137], v[224:227], v[30:33]
	v_mfma_f32_16x16x32_bf16 v[22:25], v[142:145], v[224:227], v[22:25]
	v_mfma_f32_16x16x32_bf16 v[14:17], v[134:137], v[232:235], v[14:17]
	v_mfma_f32_16x16x32_bf16 v[6:9], v[142:145], v[232:235], v[6:9]
	v_mfma_f32_16x16x32_bf16 v[58:61], v[146:149], v[162:165], v[58:61]
	v_mfma_f32_16x16x32_bf16 v[50:53], v[154:157], v[162:165], v[50:53]
	v_mfma_f32_16x16x32_bf16 v[42:45], v[146:149], v[194:197], v[42:45]
	v_mfma_f32_16x16x32_bf16 v[34:37], v[154:157], v[194:197], v[34:37]
	v_mfma_f32_16x16x32_bf16 v[26:29], v[146:149], v[202:205], v[26:29]
	v_mfma_f32_16x16x32_bf16 v[18:21], v[154:157], v[202:205], v[18:21]
	v_mfma_f32_16x16x32_bf16 v[10:13], v[146:149], v[228:231], v[10:13]
	v_mfma_f32_16x16x32_bf16 v[2:5], v[154:157], v[228:231], v[2:5]
	v_mfma_f32_16x16x32_bf16 v[58:61], v[150:153], v[166:169], v[58:61]
	v_mfma_f32_16x16x32_bf16 v[50:53], v[158:161], v[166:169], v[50:53]
	v_mfma_f32_16x16x32_bf16 v[42:45], v[150:153], v[198:201], v[42:45]
	v_mfma_f32_16x16x32_bf16 v[34:37], v[158:161], v[198:201], v[34:37]
	v_mfma_f32_16x16x32_bf16 v[26:29], v[150:153], v[224:227], v[26:29]
	v_mfma_f32_16x16x32_bf16 v[18:21], v[158:161], v[224:227], v[18:21]
	v_mfma_f32_16x16x32_bf16 v[10:13], v[150:153], v[232:235], v[10:13]
	v_mfma_f32_16x16x32_bf16 v[2:5], v[158:161], v[232:235], v[2:5]
	s_barrier
	s_add_i32 s83, s83, 2
	s_add_u32 s18, s18, 0x100
	s_addc_u32 s19, s19, 0
	s_add_u32 s54, s54, 0x100
	s_addc_u32 s81, s81, 0
	s_cmp_gt_u32 s83, 13
